# G1 static order: k-norm tile (8) swapped with tile 6 so the two-unit CUs take it
# speedup vs baseline: 1.0102x; 1.0102x over previous
.LBB0_90:
	s_add_i32 s63, s63, 1
	v_readlane_b32 s40, v252, 16
	v_readlane_b32 s42, v252, 4
	s_mul_i32 s40, s63, s40
	s_mul_hi_u32 s41, s63, s42
	s_add_i32 s41, s41, s40
	s_mul_i32 s40, s63, s42
	v_readlane_b32 s42, v252, 5
	s_add_u32 s42, s40, s42
	v_readlane_b32 s40, v252, 15
	s_addc_u32 s43, s41, s40
	v_mov_b64_e32 v[4:5], 0x240
	v_cmp_lt_i64_e64 s[40:41], s[42:43], v[4:5]
	v_mov_b64_e32 v[4:5], 0x23f
	v_cmp_gt_i64_e32 vcc, s[42:43], v[4:5]
	s_cbranch_vccnz .LBB0_92
	s_lshr_b32 s46, s42, 6
	s_mov_b32 s52, s44
	s_cmp_eq_u32 s46, 6
	s_cselect_b32 s43, 14, 0
	s_cmp_eq_u32 s46, 8
	s_cselect_b32 s43, 14, s43
	s_xor_b32 s46, s46, s43
